# mixers-A phase: workgroups without an HGRN pass-1 unit take the 4th pooling iteration and second hgrn_sample units of the others
# baseline (speedup 1.0000x reference)
.LBB0_221:
	v_mov_b32_e32 v1, v176
	v_readlane_b32 s0, v253, 5
	s_nop 1
	v_add_u32_e32 v0, s0, v1
	v_readlane_b32 s11, v252, 50
	v_readlane_b32 s13, v252, 49
	s_mov_b32 s12, 0
	s_mov_b32 s14, 0x7ffff
	s_cmpk_eq_i32 s11, 0x100
	s_cbranch_scc0 .Lrb_set
	s_mov_b32 s14, 0x5ffff
	s_cmpk_lt_i32 s13, 0xe0
	s_cbranch_scc1 .Lrb_set
	s_mov_b32 s14, 0x7ffff
	s_mov_b32 s12, 7
	s_sub_i32 s13, s13, 0xe0
	s_lshl_b32 s13, s13, 9
	s_add_i32 s13, s13, 0x60000
.Lrb_set:
	s_mov_b32 s0, 0x80000
	v_cmp_gt_i32_e32 vcc, s0, v0
	s_and_saveexec_b64 s[0:1], vcc
	s_cbranch_execz .LBB0_254
	v_readlane_b32 s2, v254, 44
	v_mov_b32_e32 v72, v0
	s_nop 0
	v_lshl_add_u32 v3, v1, 3, s2
	s_mov_b64 s[2:3], 0
	s_branch .LBB0_224
.LBB0_223:
	s_or_b64 exec, exec, s[4:5]
	s_waitcnt vmcnt(0)
	v_lshlrev_b32_e32 v71, 16, v12
	v_and_b32_e32 v12, 0xffff0000, v12
	v_add_f32_e32 v12, 0, v12
	v_lshlrev_b32_e32 v74, 16, v13
	v_and_b32_e32 v13, 0xffff0000, v13
	v_lshlrev_b32_e32 v77, 16, v8
	v_and_b32_e32 v8, 0xffff0000, v8
	v_add_f32_e32 v13, 0, v13
	v_lshlrev_b32_e32 v75, 16, v14
	v_and_b32_e32 v14, 0xffff0000, v14
	v_add_f32_e32 v8, v12, v8
	v_lshlrev_b32_e32 v12, 16, v9
	v_and_b32_e32 v9, 0xffff0000, v9
	v_add_f32_e32 v14, 0, v14
	v_lshlrev_b32_e32 v76, 16, v15
	v_and_b32_e32 v15, 0xffff0000, v15
	v_add_f32_e32 v9, v13, v9
	v_lshlrev_b32_e32 v13, 16, v10
	v_and_b32_e32 v10, 0xffff0000, v10
	v_add_f32_e32 v15, 0, v15
	v_add_f32_e32 v10, v14, v10
	v_lshlrev_b32_e32 v14, 16, v11
	v_and_b32_e32 v11, 0xffff0000, v11
	v_add_f32_e32 v74, 0, v74
	v_add_f32_e32 v11, v15, v11
	v_lshlrev_b32_e32 v15, 16, v20
	v_and_b32_e32 v20, 0xffff0000, v20
	v_add_f32_e32 v12, v74, v12
	v_add_f32_e32 v8, v8, v20
	v_lshlrev_b32_e32 v20, 16, v21
	v_add_f32_e32 v75, 0, v75
	v_add_f32_e32 v12, v12, v20
	v_and_b32_e32 v20, 0xffff0000, v21
	v_add_f32_e32 v13, v75, v13
	v_add_f32_e32 v9, v9, v20
	v_lshlrev_b32_e32 v20, 16, v22
	v_add_f32_e32 v76, 0, v76
	v_add_f32_e32 v13, v13, v20
	v_and_b32_e32 v20, 0xffff0000, v22
	v_add_f32_e32 v14, v76, v14
	v_add_f32_e32 v10, v10, v20
	v_lshlrev_b32_e32 v20, 16, v23
	v_add_f32_e32 v14, v14, v20
	v_and_b32_e32 v20, 0xffff0000, v23
	v_add_f32_e32 v11, v11, v20
	v_lshlrev_b32_e32 v20, 16, v16
	v_and_b32_e32 v16, 0xffff0000, v16
	v_add_f32_e32 v8, v8, v16
	v_lshlrev_b32_e32 v16, 16, v17
	v_add_f32_e32 v12, v12, v16
	v_and_b32_e32 v16, 0xffff0000, v17
	v_add_f32_e32 v9, v9, v16
	v_lshlrev_b32_e32 v16, 16, v18
	v_add_f32_e32 v71, 0, v71
	v_add_f32_e32 v13, v13, v16
	v_and_b32_e32 v16, 0xffff0000, v18
	v_add_f32_e32 v71, v71, v77
	v_add_f32_e32 v10, v10, v16
	v_lshlrev_b32_e32 v16, 16, v19
	v_add_f32_e32 v15, v71, v15
	v_add_f32_e32 v14, v14, v16
	v_and_b32_e32 v16, 0xffff0000, v19
	v_add_f32_e32 v15, v15, v20
	v_add_f32_e32 v11, v11, v16
	v_lshlrev_b32_e32 v16, 16, v28
	v_add_f32_e32 v15, v15, v16
	v_and_b32_e32 v16, 0xffff0000, v28
	v_add_f32_e32 v8, v8, v16
	v_lshlrev_b32_e32 v16, 16, v29
	v_add_f32_e32 v12, v12, v16
	v_and_b32_e32 v16, 0xffff0000, v29
	v_add_f32_e32 v9, v9, v16
	v_lshlrev_b32_e32 v16, 16, v30
	v_add_f32_e32 v13, v13, v16
	v_and_b32_e32 v16, 0xffff0000, v30
	v_add_f32_e32 v10, v10, v16
	v_lshlrev_b32_e32 v16, 16, v31
	v_add_f32_e32 v14, v14, v16
	v_and_b32_e32 v16, 0xffff0000, v31
	v_add_f32_e32 v11, v11, v16
	v_lshlrev_b32_e32 v16, 16, v24
	v_add_f32_e32 v15, v15, v16
	v_and_b32_e32 v16, 0xffff0000, v24
	v_add_f32_e32 v8, v8, v16
	v_lshlrev_b32_e32 v16, 16, v25
	v_add_f32_e32 v12, v12, v16
	v_and_b32_e32 v16, 0xffff0000, v25
	v_add_f32_e32 v9, v9, v16
	v_lshlrev_b32_e32 v16, 16, v26
	v_add_f32_e32 v13, v13, v16
	v_and_b32_e32 v16, 0xffff0000, v26
	v_add_f32_e32 v10, v10, v16
	v_lshlrev_b32_e32 v16, 16, v27
	v_add_f32_e32 v14, v14, v16
	v_and_b32_e32 v16, 0xffff0000, v27
	v_add_f32_e32 v11, v11, v16
	v_lshlrev_b32_e32 v16, 16, v36
	v_add_f32_e32 v15, v15, v16
	v_and_b32_e32 v16, 0xffff0000, v36
	v_add_f32_e32 v8, v8, v16
	v_lshlrev_b32_e32 v16, 16, v37
	v_add_f32_e32 v12, v12, v16
	v_and_b32_e32 v16, 0xffff0000, v37
	v_add_f32_e32 v9, v9, v16
	v_lshlrev_b32_e32 v16, 16, v38
	v_add_f32_e32 v13, v13, v16
	v_and_b32_e32 v16, 0xffff0000, v38
	v_add_f32_e32 v10, v10, v16
	v_lshlrev_b32_e32 v16, 16, v39
	v_add_f32_e32 v14, v14, v16
	v_and_b32_e32 v16, 0xffff0000, v39
	v_add_f32_e32 v11, v11, v16
	v_lshlrev_b32_e32 v16, 16, v32
	v_add_f32_e32 v15, v15, v16
	v_and_b32_e32 v16, 0xffff0000, v32
	v_add_f32_e32 v8, v8, v16
	v_lshlrev_b32_e32 v16, 16, v33
	v_add_f32_e32 v12, v12, v16
	v_and_b32_e32 v16, 0xffff0000, v33
	v_add_f32_e32 v9, v9, v16
	v_lshlrev_b32_e32 v16, 16, v34
	v_add_f32_e32 v13, v13, v16
	v_and_b32_e32 v16, 0xffff0000, v34
	v_add_f32_e32 v10, v10, v16
	v_lshlrev_b32_e32 v16, 16, v35
	v_add_f32_e32 v14, v14, v16
	v_and_b32_e32 v16, 0xffff0000, v35
	v_add_f32_e32 v11, v11, v16
	v_lshlrev_b32_e32 v16, 16, v44
	v_add_f32_e32 v15, v15, v16
	v_and_b32_e32 v16, 0xffff0000, v44
	v_add_f32_e32 v8, v8, v16
	v_lshlrev_b32_e32 v16, 16, v45
	v_add_f32_e32 v12, v12, v16
	v_and_b32_e32 v16, 0xffff0000, v45
	v_add_f32_e32 v9, v9, v16
	v_lshlrev_b32_e32 v16, 16, v46
	v_add_f32_e32 v13, v13, v16
	v_and_b32_e32 v16, 0xffff0000, v46
	v_add_f32_e32 v10, v10, v16
	v_lshlrev_b32_e32 v16, 16, v47
	v_add_f32_e32 v14, v14, v16
	v_and_b32_e32 v16, 0xffff0000, v47
	v_add_f32_e32 v11, v11, v16
	v_lshlrev_b32_e32 v16, 16, v40
	v_add_f32_e32 v15, v15, v16
	v_and_b32_e32 v16, 0xffff0000, v40
	v_add_f32_e32 v8, v8, v16
	v_lshlrev_b32_e32 v16, 16, v41
	v_add_f32_e32 v12, v12, v16
	v_and_b32_e32 v16, 0xffff0000, v41
	v_add_f32_e32 v9, v9, v16
	v_lshlrev_b32_e32 v16, 16, v42
	v_add_f32_e32 v13, v13, v16
	v_and_b32_e32 v16, 0xffff0000, v42
	v_add_f32_e32 v10, v10, v16
	v_lshlrev_b32_e32 v16, 16, v43
	v_add_f32_e32 v14, v14, v16
	v_and_b32_e32 v16, 0xffff0000, v43
	v_add_f32_e32 v11, v11, v16
	v_lshlrev_b32_e32 v16, 16, v52
	v_add_f32_e32 v15, v15, v16
	v_and_b32_e32 v16, 0xffff0000, v52
	v_add_f32_e32 v8, v8, v16
	v_lshlrev_b32_e32 v16, 16, v53
	v_add_f32_e32 v12, v12, v16
	v_and_b32_e32 v16, 0xffff0000, v53
	v_add_f32_e32 v9, v9, v16
	v_lshlrev_b32_e32 v16, 16, v54
	v_add_f32_e32 v13, v13, v16
	v_and_b32_e32 v16, 0xffff0000, v54
	v_add_f32_e32 v10, v10, v16
	v_lshlrev_b32_e32 v16, 16, v55
	v_add_f32_e32 v14, v14, v16
	v_and_b32_e32 v16, 0xffff0000, v55
	v_add_f32_e32 v11, v11, v16
	v_lshlrev_b32_e32 v16, 16, v48
	v_add_f32_e32 v15, v15, v16
	v_and_b32_e32 v16, 0xffff0000, v48
	v_add_f32_e32 v8, v8, v16
	v_lshlrev_b32_e32 v16, 16, v49
	v_add_f32_e32 v12, v12, v16
	v_and_b32_e32 v16, 0xffff0000, v49
	v_add_f32_e32 v9, v9, v16
	v_lshlrev_b32_e32 v16, 16, v50
	v_add_f32_e32 v13, v13, v16
	v_and_b32_e32 v16, 0xffff0000, v50
	v_add_f32_e32 v10, v10, v16
	v_lshlrev_b32_e32 v16, 16, v51
	v_add_f32_e32 v14, v14, v16
	v_and_b32_e32 v16, 0xffff0000, v51
	v_add_f32_e32 v11, v11, v16
	v_lshlrev_b32_e32 v16, 16, v60
	v_add_f32_e32 v15, v15, v16
	v_and_b32_e32 v16, 0xffff0000, v60
	v_add_f32_e32 v8, v8, v16
	v_lshlrev_b32_e32 v16, 16, v61
	v_add_f32_e32 v12, v12, v16
	v_and_b32_e32 v16, 0xffff0000, v61
	v_add_f32_e32 v9, v9, v16
	v_lshlrev_b32_e32 v16, 16, v62
	v_add_f32_e32 v13, v13, v16
	v_and_b32_e32 v16, 0xffff0000, v62
	v_add_f32_e32 v10, v10, v16
	v_lshlrev_b32_e32 v16, 16, v63
	v_add_f32_e32 v14, v14, v16
	v_and_b32_e32 v16, 0xffff0000, v63
	v_add_f32_e32 v11, v11, v16
	v_lshlrev_b32_e32 v16, 16, v56
	v_add_f32_e32 v15, v15, v16
	v_and_b32_e32 v16, 0xffff0000, v56
	v_add_f32_e32 v8, v8, v16
	v_lshlrev_b32_e32 v16, 16, v57
	v_add_f32_e32 v12, v12, v16
	v_and_b32_e32 v16, 0xffff0000, v57
	v_add_f32_e32 v9, v9, v16
	v_lshlrev_b32_e32 v16, 16, v58
	v_cvt_f32_ubyte0_e32 v19, v73
	v_add_f32_e32 v13, v13, v16
	v_and_b32_e32 v16, 0xffff0000, v58
	v_div_scale_f32 v20, s[4:5], v19, v19, 1.0
	v_add_f32_e32 v10, v10, v16
	v_lshlrev_b32_e32 v16, 16, v59
	v_rcp_f32_e32 v21, v20
	v_add_f32_e32 v14, v14, v16
	v_and_b32_e32 v16, 0xffff0000, v59
	v_add_f32_e32 v11, v11, v16
	v_lshlrev_b32_e32 v16, 16, v64
	v_add_f32_e32 v15, v15, v16
	v_and_b32_e32 v16, 0xffff0000, v64
	v_add_f32_e32 v8, v8, v16
	v_lshlrev_b32_e32 v16, 16, v65
	v_fma_f32 v23, -v20, v21, 1.0
	v_add_f32_e32 v12, v12, v16
	v_and_b32_e32 v16, 0xffff0000, v65
	v_fmac_f32_e32 v21, v23, v21
	v_div_scale_f32 v23, vcc, 1.0, v19, 1.0
	v_add_f32_e32 v9, v9, v16
	v_lshlrev_b32_e32 v16, 16, v66
	v_mul_f32_e32 v24, v23, v21
	v_add_f32_e32 v13, v13, v16
	v_and_b32_e32 v16, 0xffff0000, v66
	v_fma_f32 v25, -v20, v24, v23
	v_add_f32_e32 v10, v10, v16
	v_lshlrev_b32_e32 v16, 16, v67
	v_fmac_f32_e32 v24, v25, v21
	v_add_f32_e32 v14, v14, v16
	v_and_b32_e32 v16, 0xffff0000, v67
	v_fma_f32 v20, -v20, v24, v23
	v_add_f32_e32 v11, v11, v16
	v_lshlrev_b32_e32 v16, 16, v4
	v_and_b32_e32 v4, 0xffff0000, v4
	v_lshlrev_b32_e32 v17, 16, v5
	v_and_b32_e32 v5, 0xffff0000, v5
	v_div_fmas_f32 v20, v20, v21, v24
	v_lshlrev_b32_e32 v18, 16, v6
	v_and_b32_e32 v6, 0xffff0000, v6
	v_div_fixup_f32 v19, v20, v19, 1.0
	v_add_f32_e32 v8, v8, v4
	v_add_f32_e32 v9, v9, v5
	v_fma_f32 v4, v19, v8, -v4
	v_add_f32_e32 v8, v12, v17
	v_fma_f32 v5, v19, v9, -v5
	v_add_f32_e32 v9, v13, v18
	v_add_f32_e32 v10, v10, v6
	v_add_f32_e32 v15, v15, v16
	v_fma_f32 v8, v19, v8, -v17
	v_fma_f32 v9, v19, v9, -v18
	v_fma_f32 v6, v19, v10, -v6
	v_lshlrev_b32_e32 v22, 16, v7
	v_and_b32_e32 v7, 0xffff0000, v7
	v_fma_f32 v15, v19, v15, -v16
	v_cvt_pk_bf16_f32 v4, v15, v4
	v_cvt_pk_bf16_f32 v5, v8, v5
	v_cvt_pk_bf16_f32 v6, v9, v6
	v_lshlrev_b64 v[8:9], 11, v[68:69]
	v_add_u32_e32 v72, s28, v72
	s_mov_b32 s4, s14
	v_add_f32_e32 v11, v11, v7
	v_lshl_add_u64 v[8:9], s[62:63], 0, v[8:9]
	v_mov_b32_e32 v71, v2
	v_cmp_lt_i32_e32 vcc, s4, v72
	v_readlane_b32 s4, v254, 45
	v_add_f32_e32 v10, v14, v22
	v_fma_f32 v7, v19, v11, -v7
	v_lshl_add_u64 v[8:9], v[8:9], 0, v[70:71]
	s_or_b64 s[2:3], vcc, s[2:3]
	v_add_u32_e32 v3, s4, v3
	v_fma_f32 v10, v19, v10, -v22
	v_cvt_pk_bf16_f32 v7, v10, v7
	global_store_dwordx4 v[8:9], v[4:7], off offset:1024
	s_andn2_b64 exec, exec, s[2:3]
	s_cbranch_execz .LBB0_254

.LBB0_254:
	s_cmp_eq_u32 s12, 0
	s_cbranch_scc1 .Lrb_done
	s_sub_i32 s12, s12, 1
	s_or_b64 exec, exec, s[0:1]
	v_add_u32_e32 v72, s13, v1
	s_add_i32 s13, s13, 0x4000
	s_mov_b64 s[2:3], 0
	s_branch .LBB0_224

.LBB0_322:
	s_or_b64 exec, exec, s[0:1]
	v_readlane_b32 s0, v252, 50
	s_cmpk_eq_i32 s0, 0x100
	s_cbranch_scc0 .Lrb_hs_orig
	s_cmpk_lt_i32 s16, 0x100
	s_cbranch_scc0 .Lrb_hs_32
	s_movk_i32 s0, 0x200
	s_cmpk_lt_i32 s16, 32
	s_cbranch_scc0 .Lrb_hs_orig
	s_movk_i32 s0, 0x100
	s_branch .Lrb_hs_orig
.Lrb_hs_32:
	s_mov_b32 s0, 32
.Lrb_hs_orig:
	s_add_i32 s16, s16, s0
	s_cmpk_gt_i32 s16, 0x1ff
	s_barrier
	s_cbranch_scc1 .LBB0_327
